# speedup vs baseline: 1.0136x; 1.0079x over previous
; #define PG8_STAGE(bufoff, gbase, voff) do { _Pragma("unroll") for (int _i = 0; _i < 2; ++_i) \
;         __builtin_amdgcn_global_load_lds((const unsigned*)((const char*)(gbase) + (voff)[_i]), (LAS unsigned*)(lds + (bufoff) + ldsw + _i * 8192), 16, 0, 0); } while (0)
; #define PG8_LDA(dst, b, h) do { _Pragma("unroll") for (int m = 0; m < 4; ++m) _Pragma("unroll") for (int k = 0; k < 2; ++k) dst[m][k] = *(const LAS bf16x8*)(lds + PG8_SA(b, h) + aoff + m * 2048 + k * 1024); } while (0)
; #define PG8_LDB(dst, b, h) do { _Pragma("unroll") for (int n = 0; n < 2; ++n) _Pragma("unroll") for (int k = 0; k < 2; ++k) dst[n][k] = *(const LAS bf16x8*)(lds + PG8_SB(b, h) + boff + n * 2048 + k * 1024); } while (0)
; #define PG8_WAIT_L(n) asm volatile("s_waitcnt lgkmcnt(" #n ")" ::: "memory")
; #define PG8_BAR __builtin_amdgcn_s_barrier()
; #define PG8_SCHED __builtin_amdgcn_sched_barrier(0)
; __device__ __forceinline__ void gemm_phase(LAS unsigned char* lds, const GemmD& g) {
;     ...
;     for (;;) {
;         const bool has_next = unit_get(g, nM, nN, G, cblk, ui + 1, nxt);
;         const char* nA = has_next ? (const char*)g.A + (size_t)nxt.pm * tstep + (size_t)nxt.k0 * kstep : cA; const char* nB = has_next ? (const char*)g.Bt + (size_t)nxt.pn * tstep + (size_t)nxt.k0 * kstep : cB;
;         const int nt = cur.nt;
;         for (int t = 0; t < nt; t += 2) {
;             const bool last = (t == nt - 2);
;             const char* a1 = cA + (size_t)(t + 1) * kstep;
;             const char* a2 = last ? nA : cA + (size_t)(t + 2) * kstep; const char* b2 = last ? nB : cB + (size_t)(t + 2) * kstep;
;             const char* a3 = a2 + kstep; const char* b3 = b2 + kstep;
;             PG8_LDB(B0, 0, 0); PG8_SCHED; PG8_LDA(At, 0, 0); PG8_STAGE(PG8_SA(1, 1), a1 + hstep, voffA);
;             PG8_WAIT_L(8); PG8_BAR; PG8_WAIT_L(0); PG8_MMA(0, 0, At, B0); PG8_BAR; PG8_SCHED;
;             PG8_LDB(B1, 0, 1); PG8_STAGE(PG8_SB(0, 0), b2, voffB);
;     ...
;         for (int a = 0; a < 2; ++a)
; #pragma unroll
;             for (int b = 0; b < 2; ++b)
; #pragma unroll
;                 for (int m = 0; m < 4; ++m)
; #pragma unroll
;                     for (int n = 0; n < 2; ++n) acc[a][b][m][n] = (f32x4){0.f, 0.f, 0.f, 0.f};
.LBB0_144:
	v_lshl_add_u64 v[132:133], v[2:3], 0, s[46:47]
	v_mov_b32_e32 v2, 0
	v_add_u32_e32 v135, -2, v134
	v_lshl_add_u64 v[130:131], v[4:5], 0, s[44:45]
	s_mov_b32 s4, 0
	v_mov_b32_e32 v3, v2
	v_mov_b32_e32 v4, v2
	v_mov_b32_e32 v5, v2
	v_mov_b32_e32 v6, v2
	v_mov_b32_e32 v7, v2
	v_mov_b32_e32 v8, v2
	v_mov_b32_e32 v9, v2
	v_mov_b32_e32 v18, v2
	v_mov_b32_e32 v19, v2
	v_mov_b32_e32 v20, v2
	v_mov_b32_e32 v21, v2
	v_mov_b32_e32 v22, v2
	v_mov_b32_e32 v23, v2
	v_mov_b32_e32 v24, v2
	v_mov_b32_e32 v25, v2
	v_mov_b32_e32 v34, v2
	v_mov_b32_e32 v35, v2
	v_mov_b32_e32 v36, v2
	v_mov_b32_e32 v37, v2
	v_mov_b32_e32 v38, v2
	v_mov_b32_e32 v39, v2
	v_mov_b32_e32 v40, v2
	v_mov_b32_e32 v41, v2
	v_mov_b32_e32 v50, v2
	v_mov_b32_e32 v51, v2
	v_mov_b32_e32 v52, v2
	v_mov_b32_e32 v53, v2
	v_mov_b32_e32 v54, v2
	v_mov_b32_e32 v55, v2
	v_mov_b32_e32 v56, v2
	v_mov_b32_e32 v57, v2
	v_mov_b32_e32 v10, v2
	v_mov_b32_e32 v11, v2
	v_mov_b32_e32 v12, v2
	v_mov_b32_e32 v13, v2
	v_mov_b32_e32 v14, v2
	v_mov_b32_e32 v15, v2
	v_mov_b32_e32 v16, v2
	v_mov_b32_e32 v17, v2
	v_mov_b32_e32 v26, v2
	v_mov_b32_e32 v27, v2
	v_mov_b32_e32 v28, v2
	v_mov_b32_e32 v29, v2
	v_mov_b32_e32 v30, v2
	v_mov_b32_e32 v31, v2
	v_mov_b32_e32 v32, v2
	v_mov_b32_e32 v33, v2
	v_mov_b32_e32 v42, v2
	v_mov_b32_e32 v43, v2
	v_mov_b32_e32 v44, v2
	v_mov_b32_e32 v45, v2
	v_mov_b32_e32 v46, v2
	v_mov_b32_e32 v47, v2
	v_mov_b32_e32 v48, v2
	v_mov_b32_e32 v49, v2
	v_mov_b32_e32 v58, v2
	v_mov_b32_e32 v59, v2
	v_mov_b32_e32 v60, v2
	v_mov_b32_e32 v61, v2
	v_mov_b32_e32 v62, v2
	v_mov_b32_e32 v63, v2
	v_mov_b32_e32 v64, v2
	v_mov_b32_e32 v65, v2
	v_mov_b32_e32 v66, v2
	v_mov_b32_e32 v67, v2
	v_mov_b32_e32 v68, v2
	v_mov_b32_e32 v69, v2
	v_mov_b32_e32 v70, v2
	v_mov_b32_e32 v71, v2
	v_mov_b32_e32 v72, v2
	v_mov_b32_e32 v73, v2
	s_waitcnt vmcnt(0)
	v_mov_b32_e32 v82, v2
	v_mov_b32_e32 v83, v2
	v_mov_b32_e32 v84, v2
	v_mov_b32_e32 v85, v2
	v_mov_b32_e32 v86, v2
	v_mov_b32_e32 v87, v2
	v_mov_b32_e32 v88, v2
	v_mov_b32_e32 v89, v2
	v_mov_b32_e32 v98, v2
	v_mov_b32_e32 v99, v2
	v_mov_b32_e32 v100, v2
	v_mov_b32_e32 v101, v2
	v_mov_b32_e32 v102, v2
	v_mov_b32_e32 v103, v2
	v_mov_b32_e32 v104, v2
	v_mov_b32_e32 v105, v2
	v_mov_b32_e32 v114, v2
	v_mov_b32_e32 v115, v2
	v_mov_b32_e32 v116, v2
	v_mov_b32_e32 v117, v2
	v_mov_b32_e32 v118, v2
	v_mov_b32_e32 v119, v2
	v_mov_b32_e32 v120, v2
	v_mov_b32_e32 v121, v2
	v_mov_b32_e32 v74, v2
	v_mov_b32_e32 v75, v2
	v_mov_b32_e32 v76, v2
	v_mov_b32_e32 v77, v2
	v_mov_b32_e32 v78, v2
	v_mov_b32_e32 v79, v2
	v_mov_b32_e32 v80, v2
	v_mov_b32_e32 v81, v2
	v_mov_b32_e32 v90, v2
	v_mov_b32_e32 v91, v2
	v_mov_b32_e32 v92, v2
	v_mov_b32_e32 v93, v2
	v_mov_b32_e32 v94, v2
	v_mov_b32_e32 v95, v2
	v_mov_b32_e32 v96, v2
	v_mov_b32_e32 v97, v2
	v_mov_b32_e32 v106, v2
	v_mov_b32_e32 v107, v2
	v_mov_b32_e32 v108, v2
	v_mov_b32_e32 v109, v2
	v_mov_b32_e32 v110, v2
	v_mov_b32_e32 v111, v2
	v_mov_b32_e32 v112, v2
	v_mov_b32_e32 v113, v2
	v_mov_b32_e32 v122, v2
	v_mov_b32_e32 v123, v2
	v_mov_b32_e32 v124, v2
	v_mov_b32_e32 v125, v2
	v_mov_b32_e32 v126, v2
	v_mov_b32_e32 v127, v2
	v_mov_b32_e32 v128, v2
	v_mov_b32_e32 v129, v2
	v_readfirstlane_b32 s98, v130
	v_readfirstlane_b32 s99, v131
	v_readfirstlane_b32 s100, v132
	v_readfirstlane_b32 s101, v133
	v_add_u32_e32 v242, s72, v172
	v_add_u32_e32 v243, s72, v168
.LBB0_145:
	s_add_i32 s6, 0, 0x10000
	v_add_u32_e32 v148, s6, v229
	ds_read_b128 v[136:139], v148
	ds_read_b128 v[140:143], v148 offset:1024
	ds_read_b128 v[144:147], v148 offset:2048
	ds_read_b128 v[148:151], v148 offset:3072
	v_cmp_eq_u32_e32 vcc, s4, v135
	s_add_i32 s5, s4, 2
	s_add_i32 m0, s2, 0xc000
	ds_read_b128 v[152:155], v233
	ds_read_b128 v[156:159], v233 offset:1024
	ds_read_b128 v[160:163], v233 offset:2048
	ds_read_b128 v[184:187], v233 offset:3072
	ds_read_b128 v[188:191], v233 offset:4096
	ds_read_b128 v[192:195], v233 offset:5120
	ds_read_b128 v[196:199], v233 offset:6144
	ds_read_b128 v[200:203], v233 offset:7168
	global_load_lds_dwordx4 v174, s[98:99]
	s_add_i32 m0, s2, 0xe000
	s_nop 0
	global_load_lds_dwordx4 v176, s[98:99]
	s_cbranch_vccz .Lkl_notlast
	v_readfirstlane_b32 s98, v180
	v_readfirstlane_b32 s99, v181
	v_readfirstlane_b32 s100, v182
	v_readfirstlane_b32 s101, v183
	s_branch .Lkl_ptr_done
.Lkl_notlast:
	s_add_u32 s98, s98, 0x80
	s_addc_u32 s99, s99, 0
; #define PG8_STAGE(bufoff, gbase, voff) do { _Pragma("unroll") for (int _i = 0; _i < 2; ++_i) \
;         __builtin_amdgcn_global_load_lds((const unsigned*)((const char*)(gbase) + (voff)[_i]), (LAS unsigned*)(lds + (bufoff) + ldsw + _i * 8192), 16, 0, 0); } while (0)
; #define PG8_LDA(dst, b, h) do { _Pragma("unroll") for (int m = 0; m < 4; ++m) _Pragma("unroll") for (int k = 0; k < 2; ++k) dst[m][k] = *(const LAS bf16x8*)(lds + PG8_SA(b, h) + aoff + m * 2048 + k * 1024); } while (0)
; #define PG8_LDB(dst, b, h) do { _Pragma("unroll") for (int n = 0; n < 2; ++n) _Pragma("unroll") for (int k = 0; k < 2; ++k) dst[n][k] = *(const LAS bf16x8*)(lds + PG8_SB(b, h) + boff + n * 2048 + k * 1024); } while (0)
; #define PG8_MMA(ai, bj, At, Bt) do { __builtin_amdgcn_s_setprio(1); _Pragma("unroll") for (int m = 0; m < 4; ++m) _Pragma("unroll") for (int n = 0; n < 2; ++n) _Pragma("unroll") for (int k = 0; k < 2; ++k) \
;         acc[ai][bj][m][n] = __builtin_amdgcn_mfma_f32_16x16x32_bf16(Bt[n][k], At[m][k], acc[ai][bj][m][n], 0, 0, 0); __builtin_amdgcn_s_setprio(0); } while (0)
; #define PG8_WAIT_V(n) asm volatile("s_waitcnt vmcnt(" #n ")" ::: "memory")
; #define PG8_WAIT_L(n) asm volatile("s_waitcnt lgkmcnt(" #n ")" ::: "memory")
; #define PG8_BAR __builtin_amdgcn_s_barrier()
; #define PG8_SCHED __builtin_amdgcn_sched_barrier(0)
; __device__ __forceinline__ void gemm_phase(LAS unsigned char* lds, const GemmD& g) {
;     ...
;             PG8_WAIT_L(8); PG8_BAR; PG8_WAIT_L(0); PG8_MMA(0, 0, At, B0); PG8_BAR; PG8_SCHED;
;             PG8_LDB(B1, 0, 1); PG8_STAGE(PG8_SB(0, 0), b2, voffB);
;             PG8_BAR; PG8_WAIT_L(0); PG8_MMA(0, 1, At, B1); PG8_BAR;
;             PG8_LDA(At, 0, 1); PG8_STAGE(PG8_SA(0, 0), a2, voffA);
;             PG8_BAR; PG8_WAIT_L(0); PG8_MMA(1, 0, At, B0); PG8_BAR; PG8_SCHED;
;             PG8_STAGE(PG8_SB(0, 1), b2 + hstep, voffB);
;             PG8_WAIT_V(6); PG8_BAR; PG8_MMA(1, 1, At, B1); PG8_BAR;
;             PG8_LDB(B0, 1, 0); PG8_SCHED; PG8_LDA(At, 1, 0); PG8_STAGE(PG8_SA(0, 1), a2 + hstep, voffA);
;             PG8_WAIT_L(8); PG8_BAR; PG8_WAIT_L(0); PG8_MMA(0, 0, At, B0); PG8_BAR; PG8_SCHED;
;             PG8_LDB(B1, 1, 1); PG8_STAGE(PG8_SB(1, 0), b3, voffB);
;             PG8_BAR; PG8_WAIT_L(0); PG8_MMA(0, 1, At, B1); PG8_BAR;
;             PG8_LDA(At, 1, 1); PG8_STAGE(PG8_SA(1, 0), a3, voffA);
.Lkl_ptr_done:
	s_waitcnt lgkmcnt(8)
	s_barrier
	s_waitcnt lgkmcnt(0)
	v_mfma_f32_16x16x32_bf16 v[126:129], v[136:139], v[152:155], v[126:129]
	v_mfma_f32_16x16x32_bf16 v[122:125], v[144:147], v[152:155], v[122:125]
	v_mfma_f32_16x16x32_bf16 v[110:113], v[136:139], v[160:163], v[110:113]
	v_mfma_f32_16x16x32_bf16 v[106:109], v[144:147], v[160:163], v[106:109]
	v_mfma_f32_16x16x32_bf16 v[94:97], v[136:139], v[188:191], v[94:97]
	v_mfma_f32_16x16x32_bf16 v[90:93], v[144:147], v[188:191], v[90:93]
	v_mfma_f32_16x16x32_bf16 v[78:81], v[136:139], v[196:199], v[78:81]
	v_mfma_f32_16x16x32_bf16 v[74:77], v[144:147], v[196:199], v[74:77]
	v_mfma_f32_16x16x32_bf16 v[126:129], v[140:143], v[156:159], v[126:129]
	v_mfma_f32_16x16x32_bf16 v[122:125], v[148:151], v[156:159], v[122:125]
	v_mfma_f32_16x16x32_bf16 v[110:113], v[140:143], v[184:187], v[110:113]
	v_mfma_f32_16x16x32_bf16 v[106:109], v[148:151], v[184:187], v[106:109]
	v_mfma_f32_16x16x32_bf16 v[94:97], v[140:143], v[192:195], v[94:97]
	v_mfma_f32_16x16x32_bf16 v[90:93], v[148:151], v[192:195], v[90:93]
	v_mfma_f32_16x16x32_bf16 v[78:81], v[140:143], v[200:203], v[78:81]
	v_mfma_f32_16x16x32_bf16 v[74:77], v[148:151], v[200:203], v[74:77]
	s_barrier
	s_add_i32 s4, 0, 0x14000
	s_add_i32 s6, s6, s87
	v_add_u32_e32 v238, s4, v229
	s_mov_b32 m0, s6
	ds_read_b128 v[204:207], v238
	ds_read_b128 v[208:211], v238 offset:1024
	ds_read_b128 v[234:237], v238 offset:2048
	ds_read_b128 v[238:241], v238 offset:3072
	global_load_lds_dwordx4 v172, s[100:101]
	s_add_i32 m0, s6, 0x2000
	s_nop 0
	global_load_lds_dwordx4 v168, s[100:101]
	s_barrier
	s_waitcnt lgkmcnt(0)
	v_mfma_f32_16x16x32_bf16 v[118:121], v[204:207], v[152:155], v[118:121]
	v_mfma_f32_16x16x32_bf16 v[114:117], v[234:237], v[152:155], v[114:117]
	v_mfma_f32_16x16x32_bf16 v[102:105], v[204:207], v[160:163], v[102:105]
	v_mfma_f32_16x16x32_bf16 v[98:101], v[234:237], v[160:163], v[98:101]
	v_mfma_f32_16x16x32_bf16 v[86:89], v[204:207], v[188:191], v[86:89]
	v_mfma_f32_16x16x32_bf16 v[82:85], v[234:237], v[188:191], v[82:85]
	v_mfma_f32_16x16x32_bf16 v[70:73], v[204:207], v[196:199], v[70:73]
	v_mfma_f32_16x16x32_bf16 v[66:69], v[234:237], v[196:199], v[66:69]
	v_mfma_f32_16x16x32_bf16 v[118:121], v[208:211], v[156:159], v[118:121]
	v_mfma_f32_16x16x32_bf16 v[114:117], v[238:241], v[156:159], v[114:117]
	v_mfma_f32_16x16x32_bf16 v[102:105], v[208:211], v[184:187], v[102:105]
	v_mfma_f32_16x16x32_bf16 v[98:101], v[238:241], v[184:187], v[98:101]
	v_mfma_f32_16x16x32_bf16 v[86:89], v[208:211], v[192:195], v[86:89]
	v_mfma_f32_16x16x32_bf16 v[82:85], v[238:241], v[192:195], v[82:85]
	v_mfma_f32_16x16x32_bf16 v[70:73], v[208:211], v[200:203], v[70:73]
	v_mfma_f32_16x16x32_bf16 v[66:69], v[238:241], v[200:203], v[66:69]
	s_barrier
	s_mov_b32 m0, s2
	ds_read_b128 v[152:155], v233 offset:16384
	ds_read_b128 v[156:159], v233 offset:17408
	ds_read_b128 v[160:163], v233 offset:18432
	ds_read_b128 v[184:187], v233 offset:19456
	ds_read_b128 v[188:191], v233 offset:20480
	ds_read_b128 v[192:195], v233 offset:21504
	ds_read_b128 v[196:199], v233 offset:22528
	ds_read_b128 v[200:203], v233 offset:23552
	global_load_lds_dwordx4 v170, s[98:99]
	s_mov_b32 m0, s3
	s_nop 0
	global_load_lds_dwordx4 v166, s[98:99]
	s_barrier
	s_waitcnt lgkmcnt(0)
	v_mfma_f32_16x16x32_bf16 v[62:65], v[136:139], v[152:155], v[62:65]
	v_mfma_f32_16x16x32_bf16 v[58:61], v[144:147], v[152:155], v[58:61]
	v_mfma_f32_16x16x32_bf16 v[46:49], v[136:139], v[160:163], v[46:49]
	v_mfma_f32_16x16x32_bf16 v[42:45], v[144:147], v[160:163], v[42:45]
	v_mfma_f32_16x16x32_bf16 v[30:33], v[136:139], v[188:191], v[30:33]
	v_mfma_f32_16x16x32_bf16 v[26:29], v[144:147], v[188:191], v[26:29]
	v_mfma_f32_16x16x32_bf16 v[14:17], v[136:139], v[196:199], v[14:17]
	v_mfma_f32_16x16x32_bf16 v[10:13], v[144:147], v[196:199], v[10:13]
	v_mfma_f32_16x16x32_bf16 v[62:65], v[140:143], v[156:159], v[62:65]
	v_mfma_f32_16x16x32_bf16 v[58:61], v[148:151], v[156:159], v[58:61]
	v_mfma_f32_16x16x32_bf16 v[46:49], v[140:143], v[184:187], v[46:49]
	v_mfma_f32_16x16x32_bf16 v[42:45], v[148:151], v[184:187], v[42:45]
	v_mfma_f32_16x16x32_bf16 v[30:33], v[140:143], v[192:195], v[30:33]
	v_mfma_f32_16x16x32_bf16 v[26:29], v[148:151], v[192:195], v[26:29]
	v_mfma_f32_16x16x32_bf16 v[14:17], v[140:143], v[200:203], v[14:17]
	v_mfma_f32_16x16x32_bf16 v[10:13], v[148:151], v[200:203], v[10:13]
	s_barrier
	s_add_i32 s4, s4, s87
	s_mov_b32 m0, s4
	s_nop 0
	global_load_lds_dwordx4 v242, s[100:101]
	s_add_i32 m0, s4, 0x2000
	s_nop 0
	global_load_lds_dwordx4 v243, s[100:101]
	s_waitcnt vmcnt(6)
	s_barrier
	v_mfma_f32_16x16x32_bf16 v[54:57], v[204:207], v[152:155], v[54:57]
	v_mfma_f32_16x16x32_bf16 v[50:53], v[234:237], v[152:155], v[50:53]
	v_mfma_f32_16x16x32_bf16 v[38:41], v[204:207], v[160:163], v[38:41]
	v_mfma_f32_16x16x32_bf16 v[34:37], v[234:237], v[160:163], v[34:37]
	v_mfma_f32_16x16x32_bf16 v[22:25], v[204:207], v[188:191], v[22:25]
	v_mfma_f32_16x16x32_bf16 v[18:21], v[234:237], v[188:191], v[18:21]
	v_mfma_f32_16x16x32_bf16 v[6:9], v[204:207], v[196:199], v[6:9]
	v_mfma_f32_16x16x32_bf16 v[2:5], v[234:237], v[196:199], v[2:5]
	v_mfma_f32_16x16x32_bf16 v[54:57], v[208:211], v[156:159], v[54:57]
	v_mfma_f32_16x16x32_bf16 v[50:53], v[238:241], v[156:159], v[50:53]
	v_mfma_f32_16x16x32_bf16 v[38:41], v[208:211], v[184:187], v[38:41]
	v_mfma_f32_16x16x32_bf16 v[34:37], v[238:241], v[184:187], v[34:37]
	v_mfma_f32_16x16x32_bf16 v[22:25], v[208:211], v[192:195], v[22:25]
	v_mfma_f32_16x16x32_bf16 v[18:21], v[238:241], v[192:195], v[18:21]
	v_mfma_f32_16x16x32_bf16 v[6:9], v[208:211], v[200:203], v[6:9]
	v_mfma_f32_16x16x32_bf16 v[2:5], v[238:241], v[200:203], v[2:5]
	s_barrier
; #define PG8_STAGE(bufoff, gbase, voff) do { _Pragma("unroll") for (int _i = 0; _i < 2; ++_i) \
;         __builtin_amdgcn_global_load_lds((const unsigned*)((const char*)(gbase) + (voff)[_i]), (LAS unsigned*)(lds + (bufoff) + ldsw + _i * 8192), 16, 0, 0); } while (0)
; #define PG8_LDA(dst, b, h) do { _Pragma("unroll") for (int m = 0; m < 4; ++m) _Pragma("unroll") for (int k = 0; k < 2; ++k) dst[m][k] = *(const LAS bf16x8*)(lds + PG8_SA(b, h) + aoff + m * 2048 + k * 1024); } while (0)
; #define PG8_LDB(dst, b, h) do { _Pragma("unroll") for (int n = 0; n < 2; ++n) _Pragma("unroll") for (int k = 0; k < 2; ++k) dst[n][k] = *(const LAS bf16x8*)(lds + PG8_SB(b, h) + boff + n * 2048 + k * 1024); } while (0)
; #define PG8_MMA(ai, bj, At, Bt) do { __builtin_amdgcn_s_setprio(1); _Pragma("unroll") for (int m = 0; m < 4; ++m) _Pragma("unroll") for (int n = 0; n < 2; ++n) _Pragma("unroll") for (int k = 0; k < 2; ++k) \
;         acc[ai][bj][m][n] = __builtin_amdgcn_mfma_f32_16x16x32_bf16(Bt[n][k], At[m][k], acc[ai][bj][m][n], 0, 0, 0); __builtin_amdgcn_s_setprio(0); } while (0)
; #define PG8_WAIT_V(n) asm volatile("s_waitcnt vmcnt(" #n ")" ::: "memory")
; #define PG8_WAIT_L(n) asm volatile("s_waitcnt lgkmcnt(" #n ")" ::: "memory")
; #define PG8_BAR __builtin_amdgcn_s_barrier()
; #define PG8_SCHED __builtin_amdgcn_sched_barrier(0)
; __device__ __forceinline__ void gemm_phase(LAS unsigned char* lds, const GemmD& g) {
;     ...
;             PG8_LDB(B0, 1, 0); PG8_SCHED; PG8_LDA(At, 1, 0); PG8_STAGE(PG8_SA(0, 1), a2 + hstep, voffA);
;             PG8_WAIT_L(8); PG8_BAR; PG8_WAIT_L(0); PG8_MMA(0, 0, At, B0); PG8_BAR; PG8_SCHED;
;             PG8_LDB(B1, 1, 1); PG8_STAGE(PG8_SB(1, 0), b3, voffB);
;             PG8_BAR; PG8_WAIT_L(0); PG8_MMA(0, 1, At, B1); PG8_BAR;
;             PG8_LDA(At, 1, 1); PG8_STAGE(PG8_SA(1, 0), a3, voffA);
;             PG8_BAR; PG8_WAIT_L(0); PG8_MMA(1, 0, At, B0); PG8_BAR; PG8_SCHED;
;             PG8_STAGE(PG8_SB(1, 1), b3 + hstep, voffB);
;             PG8_WAIT_V(6); PG8_BAR; PG8_MMA(1, 1, At, B1); PG8_BAR;
;         }
	s_add_i32 s4, 0, 0x18000
	v_add_u32_e32 v148, s4, v229
	ds_read_b128 v[136:139], v148
	ds_read_b128 v[140:143], v148 offset:1024
	ds_read_b128 v[144:147], v148 offset:2048
	ds_read_b128 v[148:151], v148 offset:3072
	s_mov_b32 m0, s64
	ds_read_b128 v[152:155], v233 offset:32768
	ds_read_b128 v[156:159], v233 offset:33792
	ds_read_b128 v[160:163], v233 offset:34816
	ds_read_b128 v[184:187], v233 offset:35840
	ds_read_b128 v[188:191], v233 offset:36864
	ds_read_b128 v[192:195], v233 offset:37888
	ds_read_b128 v[196:199], v233 offset:38912
	ds_read_b128 v[200:203], v233 offset:39936
	global_load_lds_dwordx4 v174, s[98:99]
	s_mov_b32 m0, s65
	s_nop 0
	global_load_lds_dwordx4 v176, s[98:99]
	s_waitcnt lgkmcnt(8)
	s_barrier
	s_waitcnt lgkmcnt(0)
	v_mfma_f32_16x16x32_bf16 v[126:129], v[136:139], v[152:155], v[126:129]
	v_mfma_f32_16x16x32_bf16 v[122:125], v[144:147], v[152:155], v[122:125]
	v_mfma_f32_16x16x32_bf16 v[110:113], v[136:139], v[160:163], v[110:113]
	v_mfma_f32_16x16x32_bf16 v[106:109], v[144:147], v[160:163], v[106:109]
	v_mfma_f32_16x16x32_bf16 v[94:97], v[136:139], v[188:191], v[94:97]
	v_mfma_f32_16x16x32_bf16 v[90:93], v[144:147], v[188:191], v[90:93]
	v_mfma_f32_16x16x32_bf16 v[78:81], v[136:139], v[196:199], v[78:81]
	v_mfma_f32_16x16x32_bf16 v[74:77], v[144:147], v[196:199], v[74:77]
	v_mfma_f32_16x16x32_bf16 v[126:129], v[140:143], v[156:159], v[126:129]
	v_mfma_f32_16x16x32_bf16 v[122:125], v[148:151], v[156:159], v[122:125]
	v_mfma_f32_16x16x32_bf16 v[110:113], v[140:143], v[184:187], v[110:113]
	v_mfma_f32_16x16x32_bf16 v[106:109], v[148:151], v[184:187], v[106:109]
	v_mfma_f32_16x16x32_bf16 v[94:97], v[140:143], v[192:195], v[94:97]
	v_mfma_f32_16x16x32_bf16 v[90:93], v[148:151], v[192:195], v[90:93]
	v_mfma_f32_16x16x32_bf16 v[78:81], v[140:143], v[200:203], v[78:81]
	v_mfma_f32_16x16x32_bf16 v[74:77], v[148:151], v[200:203], v[74:77]
	s_barrier
	s_add_i32 s6, 0, 0x1c000
	v_add_u32_e32 v164, s6, v229
	s_add_i32 s4, s4, s87
	ds_read_b128 v[204:207], v164
	ds_read_b128 v[208:211], v164 offset:1024
	ds_read_b128 v[234:237], v164 offset:2048
	ds_read_b128 v[238:241], v164 offset:3072
	s_add_u32 s100, s100, 0x80
	s_addc_u32 s101, s101, 0
	s_mov_b32 m0, s4
	s_nop 0
	global_load_lds_dwordx4 v172, s[100:101]
	s_add_i32 m0, s4, 0x2000
	s_nop 0
	global_load_lds_dwordx4 v168, s[100:101]
	s_barrier
	s_waitcnt lgkmcnt(0)
	v_mfma_f32_16x16x32_bf16 v[118:121], v[204:207], v[152:155], v[118:121]
	v_mfma_f32_16x16x32_bf16 v[114:117], v[234:237], v[152:155], v[114:117]
	v_mfma_f32_16x16x32_bf16 v[102:105], v[204:207], v[160:163], v[102:105]
	v_mfma_f32_16x16x32_bf16 v[98:101], v[234:237], v[160:163], v[98:101]
	v_mfma_f32_16x16x32_bf16 v[86:89], v[204:207], v[188:191], v[86:89]
	v_mfma_f32_16x16x32_bf16 v[82:85], v[234:237], v[188:191], v[82:85]
	v_mfma_f32_16x16x32_bf16 v[70:73], v[204:207], v[196:199], v[70:73]
	v_mfma_f32_16x16x32_bf16 v[66:69], v[234:237], v[196:199], v[66:69]
	v_mfma_f32_16x16x32_bf16 v[118:121], v[208:211], v[156:159], v[118:121]
	v_mfma_f32_16x16x32_bf16 v[114:117], v[238:241], v[156:159], v[114:117]
	v_mfma_f32_16x16x32_bf16 v[102:105], v[208:211], v[184:187], v[102:105]
	v_mfma_f32_16x16x32_bf16 v[98:101], v[238:241], v[184:187], v[98:101]
	v_mfma_f32_16x16x32_bf16 v[86:89], v[208:211], v[192:195], v[86:89]
	v_mfma_f32_16x16x32_bf16 v[82:85], v[238:241], v[192:195], v[82:85]
	v_mfma_f32_16x16x32_bf16 v[70:73], v[208:211], v[200:203], v[70:73]
	v_mfma_f32_16x16x32_bf16 v[66:69], v[238:241], v[200:203], v[66:69]
	s_barrier
	s_mov_b32 m0, s28
	s_add_u32 s98, s98, 0x80
	s_addc_u32 s99, s99, 0
	ds_read_b128 v[152:155], v233 offset:49152
	ds_read_b128 v[156:159], v233 offset:50176
	ds_read_b128 v[160:163], v233 offset:51200
	ds_read_b128 v[184:187], v233 offset:52224
	ds_read_b128 v[188:191], v233 offset:53248
	ds_read_b128 v[192:195], v233 offset:54272
	ds_read_b128 v[196:199], v233 offset:55296
	ds_read_b128 v[200:203], v233 offset:56320
	global_load_lds_dwordx4 v170, s[98:99]
	s_mov_b32 m0, s29
	s_nop 0
	global_load_lds_dwordx4 v166, s[98:99]
	s_barrier
	s_waitcnt lgkmcnt(0)
	v_mfma_f32_16x16x32_bf16 v[62:65], v[136:139], v[152:155], v[62:65]
	v_mfma_f32_16x16x32_bf16 v[58:61], v[144:147], v[152:155], v[58:61]
	v_mfma_f32_16x16x32_bf16 v[46:49], v[136:139], v[160:163], v[46:49]
	v_mfma_f32_16x16x32_bf16 v[42:45], v[144:147], v[160:163], v[42:45]
	v_mfma_f32_16x16x32_bf16 v[30:33], v[136:139], v[188:191], v[30:33]
	v_mfma_f32_16x16x32_bf16 v[26:29], v[144:147], v[188:191], v[26:29]
	v_mfma_f32_16x16x32_bf16 v[14:17], v[136:139], v[196:199], v[14:17]
	v_mfma_f32_16x16x32_bf16 v[10:13], v[144:147], v[196:199], v[10:13]
	v_mfma_f32_16x16x32_bf16 v[62:65], v[140:143], v[156:159], v[62:65]
	v_mfma_f32_16x16x32_bf16 v[58:61], v[148:151], v[156:159], v[58:61]
	v_mfma_f32_16x16x32_bf16 v[46:49], v[140:143], v[184:187], v[46:49]
	v_mfma_f32_16x16x32_bf16 v[42:45], v[148:151], v[184:187], v[42:45]
	v_mfma_f32_16x16x32_bf16 v[30:33], v[140:143], v[192:195], v[30:33]
	v_mfma_f32_16x16x32_bf16 v[26:29], v[148:151], v[192:195], v[26:29]
	v_mfma_f32_16x16x32_bf16 v[14:17], v[140:143], v[200:203], v[14:17]
	v_mfma_f32_16x16x32_bf16 v[10:13], v[148:151], v[200:203], v[10:13]
	s_barrier
	s_add_i32 s4, s6, s87
	s_mov_b32 m0, s4
	s_nop 0
	global_load_lds_dwordx4 v242, s[100:101]
	s_add_i32 m0, s4, 0x2000
	s_nop 0
	global_load_lds_dwordx4 v243, s[100:101]
	s_add_u32 s100, s100, 0x80
	s_addc_u32 s101, s101, 0
	v_cmp_ge_u32_e32 vcc, s5, v134
	s_mov_b32 s4, s5
	s_waitcnt vmcnt(6)
	s_barrier
	v_mfma_f32_16x16x32_bf16 v[54:57], v[204:207], v[152:155], v[54:57]
	v_mfma_f32_16x16x32_bf16 v[50:53], v[234:237], v[152:155], v[50:53]
	v_mfma_f32_16x16x32_bf16 v[38:41], v[204:207], v[160:163], v[38:41]
	v_mfma_f32_16x16x32_bf16 v[34:37], v[234:237], v[160:163], v[34:37]
	v_mfma_f32_16x16x32_bf16 v[22:25], v[204:207], v[188:191], v[22:25]
	v_mfma_f32_16x16x32_bf16 v[18:21], v[234:237], v[188:191], v[18:21]
	v_mfma_f32_16x16x32_bf16 v[6:9], v[204:207], v[196:199], v[6:9]
	v_mfma_f32_16x16x32_bf16 v[2:5], v[234:237], v[196:199], v[2:5]
	v_mfma_f32_16x16x32_bf16 v[54:57], v[208:211], v[156:159], v[54:57]
	v_mfma_f32_16x16x32_bf16 v[50:53], v[238:241], v[156:159], v[50:53]
	v_mfma_f32_16x16x32_bf16 v[38:41], v[208:211], v[184:187], v[38:41]
	v_mfma_f32_16x16x32_bf16 v[34:37], v[238:241], v[184:187], v[34:37]
	v_mfma_f32_16x16x32_bf16 v[22:25], v[208:211], v[192:195], v[22:25]
	v_mfma_f32_16x16x32_bf16 v[18:21], v[238:241], v[192:195], v[18:21]
	v_mfma_f32_16x16x32_bf16 v[6:9], v[208:211], v[200:203], v[6:9]
	v_mfma_f32_16x16x32_bf16 v[2:5], v[238:241], v[200:203], v[2:5]
	s_barrier
	s_cbranch_vccz .LBB0_145
	v_lshl_add_u32 v184, s56, 8, v228
	s_cmp_lt_i32 s66, 0
	s_mov_b64 s[4:5], -1
	s_cbranch_scc0 .LBB0_704
